# cooperative-groups grid.sync body replaced by a hand-written first use of the XCD-hierarchical barrier (same counters/protocol as the later barriers)
# speedup vs baseline: 1.0348x; 1.0263x over previous
.LBB0_91:
	s_or_b64 exec, exec, s[10:11]
	v_lshrrev_b32_e32 v1, 20, v0
	v_lshrrev_b32_e32 v0, 10, v0
	v_or_b32_e32 v0, v0, v1
	s_movk_i32 s1, 0x3ff
	v_and_or_b32 v0, v0, s1, v181
	v_cmp_eq_u32_e32 vcc, 0, v0
	s_waitcnt vmcnt(0) lgkmcnt(0)
	s_barrier
	s_and_saveexec_b64 s[4:5], vcc
	s_cbranch_execz .LBB0_101
	s_lshl_b32 s1, s0, 8
	s_add_u32 s6, s56, s1
	s_addc_u32 s7, s57, 0
	s_add_u32 s8, s56, 0x1000
	s_addc_u32 s9, s57, 0
	v_mov_b32_e32 v1, 0
	s_mov_b32 s1, 0
.Lgb_count:
	global_load_dword v2, v1, s[56:57] offset:1024 sc1
	global_load_dword v3, v1, s[56:57] offset:1280 sc1
	global_load_dword v4, v1, s[56:57] offset:1536 sc1
	global_load_dword v5, v1, s[56:57] offset:1792 sc1
	global_load_dword v6, v1, s[56:57] offset:2048 sc1
	global_load_dword v7, v1, s[56:57] offset:2304 sc1
	global_load_dword v8, v1, s[56:57] offset:2560 sc1
	global_load_dword v9, v1, s[56:57] offset:2816 sc1
	global_load_dword v10, v1, s[56:57] offset:3072 sc1
	global_load_dword v11, v1, s[56:57] offset:3328 sc1
	global_load_dword v12, v1, s[56:57] offset:3584 sc1
	global_load_dword v13, v1, s[56:57] offset:3840 sc1
	global_load_dword v14, v1, s[8:9] sc1
	global_load_dword v15, v1, s[8:9] offset:256 sc1
	global_load_dword v16, v1, s[8:9] offset:512 sc1
	global_load_dword v17, v1, s[8:9] offset:768 sc1
	global_load_dword v18, v1, s[6:7] offset:1024 sc1
	s_waitcnt vmcnt(0)
	v_add3_u32 v0, v2, v3, v4
	v_add3_u32 v0, v0, v5, v6
	v_add3_u32 v0, v0, v7, v8
	v_add3_u32 v0, v0, v9, v10
	v_add3_u32 v0, v0, v11, v12
	v_add3_u32 v0, v0, v13, v14
	v_add3_u32 v0, v0, v15, v16
	v_add_u32_e32 v0, v0, v17
	v_cmp_eq_u32_e32 vcc, s50, v0
	s_cbranch_vccnz .Lgb_ready
	s_sleep 1
	s_add_i32 s1, s1, 1
	s_cmp_lt_u32 s1, 0x4000
	s_cbranch_scc1 .Lgb_count
.Lgb_ready:
	v_min_u32_e32 v2, 1, v2
	v_min_u32_e32 v3, 1, v3
	v_min_u32_e32 v4, 1, v4
	v_min_u32_e32 v5, 1, v5
	v_min_u32_e32 v6, 1, v6
	v_min_u32_e32 v7, 1, v7
	v_min_u32_e32 v8, 1, v8
	v_min_u32_e32 v9, 1, v9
	v_min_u32_e32 v10, 1, v10
	v_min_u32_e32 v11, 1, v11
	v_min_u32_e32 v12, 1, v12
	v_min_u32_e32 v13, 1, v13
	v_min_u32_e32 v14, 1, v14
	v_min_u32_e32 v15, 1, v15
	v_min_u32_e32 v16, 1, v16
	v_min_u32_e32 v17, 1, v17
	v_add3_u32 v0, v2, v3, v4
	v_add3_u32 v0, v0, v5, v6
	v_add3_u32 v0, v0, v7, v8
	v_add3_u32 v0, v0, v9, v10
	v_add3_u32 v0, v0, v11, v12
	v_add3_u32 v0, v0, v13, v14
	v_add3_u32 v0, v0, v15, v16
	v_add_u32_e32 v0, v0, v17
	v_max_u32_e32 v0, 1, v0
	v_max_u32_e32 v18, 1, v18
	v_mov_b32_e32 v2, 0x24010
	ds_write_b32 v2, v18
	ds_write_b32 v2, v0 offset:4
	s_add_u32 s10, s6, 0x1000
	s_addc_u32 s11, s7, 0
	s_add_u32 s8, s6, 0x2000
	s_addc_u32 s9, s7, 0
	s_add_u32 s12, s56, 0x3000
	s_addc_u32 s13, s57, 0
	v_mov_b32_e32 v2, 1
	global_atomic_add v3, v1, v2, s[10:11] offset:1024 sc0
	s_waitcnt vmcnt(0)
	v_add_u32_e32 v3, 1, v3
	v_cmp_ne_u32_e32 vcc, v3, v18
	s_cbranch_vccnz .Lgb_follow
	buffer_wbl2 sc1
	s_waitcnt vmcnt(0) lgkmcnt(0)
	global_atomic_add v3, v1, v2, s[12:13] offset:1024 sc0
	s_waitcnt vmcnt(0)
	v_add_u32_e32 v3, 1, v3
	v_cmp_ne_u32_e32 vcc, v3, v0
	s_cbranch_vccnz .Lgb_topwait
	global_atomic_add v1, v2, s[12:13] offset:1280
	s_branch .Lgb_topdone
.Lgb_topwait:
	s_mov_b32 s1, 0
.Lgb_topspin:
	s_sleep 1
	global_load_dword v3, v1, s[12:13] offset:1280 sc1
	s_add_i32 s1, s1, 1
	s_waitcnt vmcnt(0)
	v_cmp_ne_u32_e32 vcc, 0, v3
	s_cbranch_vccnz .Lgb_topdone
	s_cmp_lt_u32 s1, 0x4000
	s_cbranch_scc1 .Lgb_topspin
.Lgb_topdone:
	s_waitcnt vmcnt(0)
	buffer_inv sc1
	global_atomic_add v1, v2, s[8:9] offset:1024
	s_waitcnt vmcnt(0)
	s_branch .LBB0_101

.Lgb_fspin:
	s_sleep 1
	global_load_dword v3, v1, s[8:9] offset:1024 sc1
	s_add_i32 s1, s1, 1
	s_waitcnt vmcnt(0)
	v_cmp_ne_u32_e32 vcc, 0, v3
	s_cbranch_vccnz .Lgb_fdone
	s_cmp_lt_u32 s1, 0x4000
	s_cbranch_scc1 .Lgb_fspin
.Lgb_fdone:
	buffer_inv sc1
	s_waitcnt vmcnt(0)
